# m21 + non-temporal hint also on the final RMSNorm H loads
# speedup vs baseline: 1.0047x; 1.0022x over previous
; __device__ __forceinline__ float rstd_of(const unsigned long long* ssq, int row) { return rsqrtf((float)ssq[row] * (1.0f / (SSQ_SCALE * 1024.0f)) + EPS); }
; __global__ void __launch_bounds__(512, 2) mk_fwd(Args a) {
;     ...
;     if (IN(8)) {
;         const float* gf = a.in[22];
;         for (int orow0 = gw * 4; orow0 < NOUT_ROWS; orow0 += NGW * 4) {
;             u32x4 hv[4][2]; float rs[4];
; #pragma unroll
;             for (int i = 0; i < 4; ++i) { const int row = orow0 + i;
;                 rs[i] = rstd_of(SSQ3, row);
; #pragma unroll
;                 for (int j = 0; j < 2; ++j) hv[i][j] = *(const u32x4*)(H + (size_t)row * D + (j * 64 + lane) * 8); }
.LBB0_712:
	s_cmp_lt_i32 s30, 9
	s_cselect_b64 s[2:3], -1, 0
	s_cmp_gt_i32 s31, 8
	v_readlane_b32 s8, v254, 0
	s_cselect_b64 s[4:5], -1, 0
	s_cmpk_lt_i32 s8, 0x6000
	s_cselect_b64 s[6:7], -1, 0
	s_and_b64 s[2:3], s[2:3], s[6:7]
	s_and_b64 s[2:3], s[2:3], s[4:5]
	s_and_b64 vcc, exec, s[2:3]
	s_cbranch_vccz .LBB0_715
	s_load_dwordx4 s[12:15], s[0:1], 0xb0
	s_lshl_b32 s6, s8, 2
	s_ashr_i32 s7, s6, 31
	v_lshlrev_b32_e32 v24, 4, v203
	v_mov_b32_e32 v25, 0
	s_ashr_i32 s45, s44, 31
	s_lshl_b64 s[0:1], s[6:7], 11
	v_and_b32_e32 v0, 63, v202
	s_waitcnt lgkmcnt(0)
	v_lshl_add_u64 v[26:27], s[12:13], 0, v[24:25]
	s_lshl_b64 s[8:9], s[6:7], 3
	s_lshl_b64 s[10:11], s[44:45], 3
	v_lshl_or_b32 v48, v0, 3, s0
	v_mov_b32_e32 v49, s1
	s_lshl_b64 s[12:13], s[44:45], 11
	s_lshl_b64 s[0:1], s[6:7], 12
	s_add_u32 s0, s14, s0
	v_lshlrev_b32_e32 v24, 4, v0
	s_addc_u32 s1, s15, s1
	v_lshl_add_u64 v[50:51], s[0:1], 0, v[24:25]
	s_lshl_b64 s[14:15], s[44:45], 12
	v_mov_b32_e32 v68, 0x358637bd
	s_mov_b32 s7, 0x800000
	s_add_u32 s16, s28, 0x3200000
	s_addc_u32 s17, s29, 0
	v_lshl_add_u64 v[48:49], s[16:17], 0, v[48:49]
	s_add_u32 s0, s28, s8
	s_addc_u32 s1, s29, s9
	s_add_u32 s0, s0, 0x400000
	s_addc_u32 s1, s1, 0
	global_load_dwordx4 v[88:91], v[26:27], off
	global_load_dwordx4 v[92:95], v[26:27], off offset:1024
	global_load_dwordx4 v[96:99], v[26:27], off offset:2048
	global_load_dwordx4 v[100:103], v[26:27], off offset:3072
	v_add_co_u32_e32 v52, vcc, 0x1000, v48
	s_nop 1
	v_addc_co_u32_e32 v53, vcc, 0, v49, vcc
	global_load_dwordx4 v[136:139], v25, s[0:1]
	global_load_dwordx4 v[140:143], v25, s[0:1] offset:16
	global_load_dwordx2 v[104:105], v[48:49], off nt
	global_load_dwordx2 v[106:107], v[48:49], off offset:512 nt
	global_load_dwordx2 v[108:109], v[48:49], off offset:1024 nt
	global_load_dwordx2 v[110:111], v[48:49], off offset:1536 nt
	global_load_dwordx2 v[112:113], v[48:49], off offset:2048 nt
	global_load_dwordx2 v[114:115], v[48:49], off offset:2560 nt
	global_load_dwordx2 v[116:117], v[48:49], off offset:3072 nt
	global_load_dwordx2 v[118:119], v[48:49], off offset:3584 nt
	global_load_dwordx2 v[120:121], v[52:53], off nt
	global_load_dwordx2 v[122:123], v[52:53], off offset:512 nt
	global_load_dwordx2 v[124:125], v[52:53], off offset:1024 nt
	global_load_dwordx2 v[126:127], v[52:53], off offset:1536 nt
	global_load_dwordx2 v[128:129], v[52:53], off offset:2048 nt
	global_load_dwordx2 v[130:131], v[52:53], off offset:2560 nt
	global_load_dwordx2 v[132:133], v[52:53], off offset:3072 nt
	global_load_dwordx2 v[134:135], v[52:53], off offset:3584 nt
	s_waitcnt vmcnt(0)
	s_branch .Lp8_entry

; __device__ __forceinline__ float rstd_of(const unsigned long long* ssq, int row) { return rsqrtf((float)ssq[row] * (1.0f / (SSQ_SCALE * 1024.0f)) + EPS); }
; __global__ void __launch_bounds__(512, 2) mk_fwd(Args a) {
;     ...
;         for (int orow0 = gw * 4; orow0 < NOUT_ROWS; orow0 += NGW * 4) {
;             u32x4 hv[4][2]; float rs[4];
; #pragma unroll
;             for (int i = 0; i < 4; ++i) { const int row = orow0 + i;
;                 rs[i] = rstd_of(SSQ3, row);
; #pragma unroll
;                 for (int j = 0; j < 2; ++j) hv[i][j] = *(const u32x4*)(H + (size_t)row * D + (j * 64 + lane) * 8); }
.Lp8_entry:
	v_mov_b64_e32 v[144:145], v[104:105]
	v_mov_b64_e32 v[146:147], v[106:107]
	v_mov_b64_e32 v[148:149], v[108:109]
	v_mov_b64_e32 v[150:151], v[110:111]
	v_mov_b64_e32 v[152:153], v[112:113]
	v_mov_b64_e32 v[154:155], v[114:115]
	v_mov_b64_e32 v[156:157], v[116:117]
	v_mov_b64_e32 v[158:159], v[118:119]
	v_mov_b64_e32 v[160:161], v[120:121]
	v_mov_b64_e32 v[162:163], v[122:123]
	v_mov_b64_e32 v[164:165], v[124:125]
	v_mov_b64_e32 v[166:167], v[126:127]
	v_mov_b64_e32 v[168:169], v[128:129]
	v_mov_b64_e32 v[170:171], v[130:131]
	v_mov_b64_e32 v[172:173], v[132:133]
	v_mov_b64_e32 v[174:175], v[134:135]
	v_mov_b64_e32 v[176:177], v[136:137]
	v_mov_b64_e32 v[178:179], v[138:139]
	v_mov_b64_e32 v[180:181], v[140:141]
	v_mov_b64_e32 v[182:183], v[142:143]
	s_add_i32 s6, s6, s44
	s_add_u32 s0, s0, s10
	s_addc_u32 s1, s1, s11
	v_lshl_add_u64 v[48:49], v[48:49], 0, s[12:13]
	s_cmp_lt_i32 s6, 0x18000
	s_cbranch_scc0 .Lp8_noload
	v_add_co_u32_e32 v52, vcc, 0x1000, v48
	s_nop 1
	v_addc_co_u32_e32 v53, vcc, 0, v49, vcc
	global_load_dwordx4 v[136:139], v25, s[0:1]
	global_load_dwordx4 v[140:143], v25, s[0:1] offset:16
	global_load_dwordx2 v[104:105], v[48:49], off nt
	global_load_dwordx2 v[106:107], v[48:49], off offset:512 nt
	global_load_dwordx2 v[108:109], v[48:49], off offset:1024 nt
	global_load_dwordx2 v[110:111], v[48:49], off offset:1536 nt
	global_load_dwordx2 v[112:113], v[48:49], off offset:2048 nt
	global_load_dwordx2 v[114:115], v[48:49], off offset:2560 nt
	global_load_dwordx2 v[116:117], v[48:49], off offset:3072 nt
	global_load_dwordx2 v[118:119], v[48:49], off offset:3584 nt
	global_load_dwordx2 v[120:121], v[52:53], off nt
	global_load_dwordx2 v[122:123], v[52:53], off offset:512 nt
	global_load_dwordx2 v[124:125], v[52:53], off offset:1024 nt
	global_load_dwordx2 v[126:127], v[52:53], off offset:1536 nt
	global_load_dwordx2 v[128:129], v[52:53], off offset:2048 nt
	global_load_dwordx2 v[130:131], v[52:53], off offset:2560 nt
	global_load_dwordx2 v[132:133], v[52:53], off offset:3072 nt
	global_load_dwordx2 v[134:135], v[52:53], off offset:3584 nt
